# fixup loop rewritten: all 20 loads of an item issued up front, one wait
# speedup vs baseline: 1.0022x; 1.0022x over previous
; __device__ __forceinline__ int lnd_tid() { int t = threadIdx.x; asm volatile("" : "+v"(t)); return t; }
; #define GAS __attribute__((address_space(1)))
; __device__ void lru_fixup_phase(const Params& p) {
;     ...
;     for (int i = blockIdx.x * 512 + lnd_tid(); i < (NT / 4) * 256; i += gridDim.x * 512) {
;         const int tg = i >> 8, c8 = (i & 255) * 8, tile = tg >> 3; const size_t o4 = ((size_t)tg * DM + c8) * 4;
;         f16x8 hl[4], pf[4], pb[4], y[4];
; #pragma unroll
;         for (int q = 0; q < 4; ++q) { hl[q] = *(const GAS f16x8*)(HL + o4 + 8 * q); pf[q] = *(const GAS f16x8*)(PF + o4 + 8 * q); pb[q] = *(const GAS f16x8*)(PB + o4 + 8 * q); y[q] = *(const GAS f16x8*)(YB + (size_t)(4 * tg + q) * DM + c8); }
;         const GAS float* cf = carry + (size_t)(tile * 2) * 2048 + c8; const GAS float* cbk = cf + 2048;
;         const f32x4 cf0 = *(const GAS f32x4*)cf, cf1 = *(const GAS f32x4*)(cf + 4), cb0 = *(const GAS f32x4*)cbk, cb1 = *(const GAS f32x4*)(cbk + 4);
; #pragma unroll
;         for (int r = 0; r < 4; ++r) {
;             float v[8];
; #pragma unroll
;             for (int j = 0; j < 8; ++j) { const float cfj = j < 4 ? cf0[j & 3] : cf1[j & 3], cbj = j < 4 ? cb0[j & 3] : cb1[j & 3]; const int e = (j & 1) * 4 + r;
;                 v[j] = (float)y[r][j] * ((float)hl[j >> 1][e] + (float)pf[j >> 1][e] * cfj + (float)pb[j >> 1][e] * cbj); }
;             u32x4 wv; wv.x = pk2(v[0], v[1]); wv.y = pk2(v[2], v[3]); wv.z = pk2(v[4], v[5]); wv.w = pk2(v[6], v[7]);
;             *(GAS u32x4*)(out + (size_t)(4 * tg + r) * DM + c8) = wv;
.LBB0_466:
	s_or_b64 exec, exec, s[0:1]
	s_mov_b64 s[14:15], s[68:69]
	v_mov_b32_e32 v2, v252
	v_readlane_b32 s0, v254, 1
	s_waitcnt lgkmcnt(0)
	s_barrier
	s_nop 0
	v_add_u32_e32 v1, s0, v2
	s_mov_b32 s0, 0x100000
	v_cmp_gt_i32_e32 vcc, s0, v1
	s_and_saveexec_b64 s[0:1], vcc
	s_cbranch_execz .LBB0_469
	s_add_u32 s4, s14, 0x10ac5000
	s_addc_u32 s5, s15, 0
	s_add_u32 s6, s14, 0x18ac4000
	s_addc_u32 s7, s15, 0
	s_add_u32 s8, s14, 0x1cac4000
	s_addc_u32 s9, s15, 0
	s_add_u32 s10, s14, 0x20ac4000
	s_addc_u32 s11, s15, 0
	s_add_u32 s12, s14, 0xc200000
	s_addc_u32 s13, s15, 0
	s_add_u32 s14, s14, 0xcac5000
	v_readlane_b32 s18, v254, 21
	s_addc_u32 s15, s15, 0
	s_mov_b64 s[20:21], 0
	v_lshl_add_u32 v14, v2, 3, s18
.Lfix_loop:
	v_ashrrev_i32_e32 v2, 8, v1
	v_and_b32_e32 v6, 0x7f8, v14
	v_ashrrev_i32_e32 v3, 31, v2
	v_lshlrev_b64 v[4:5], 14, v[2:3]
	v_lshlrev_b32_e32 v8, 1, v6
	v_mov_b32_e32 v9, v0
	v_lshl_add_u64 v[10:11], s[4:5], 0, v[8:9]
	v_lshl_add_u64 v[10:11], v[10:11], 0, v[4:5]
	global_load_dwordx4 v[16:19], v[10:11], off offset:-4096
	global_load_dwordx4 v[20:23], v[10:11], off
	v_lshl_add_u64 v[12:13], v[10:11], 0, s[52:53]
	global_load_dwordx4 v[24:27], v[12:13], off offset:-4096
	global_load_dwordx4 v[28:31], v[12:13], off
	v_lshl_add_u64 v[96:97], s[14:15], 0, v[8:9]
	v_lshl_add_u64 v[96:97], v[96:97], 0, v[4:5]
	v_lshl_add_u64 v[98:99], v[96:97], 0, s[52:53]
	v_ashrrev_i32_e32 v2, 11, v1
	v_ashrrev_i32_e32 v3, 31, v2
	v_lshlrev_b64 v[2:3], 14, v[2:3]
	v_lshlrev_b32_e32 v8, 2, v6
	v_lshl_add_u64 v[10:11], s[12:13], 0, v[8:9]
	v_lshl_add_u64 v[10:11], v[10:11], 0, v[2:3]
	global_load_dwordx4 v[32:35], v[10:11], off
	global_load_dwordx4 v[36:39], v[10:11], off offset:16
	v_lshl_add_u64 v[12:13], v[10:11], 0, s[52:53]
	global_load_dwordx4 v[40:43], v[12:13], off
	global_load_dwordx4 v[44:47], v[12:13], off offset:16
	v_lshl_or_b32 v8, v6, 3, v4
	v_mov_b32_e32 v9, v5
	v_lshl_add_u64 v[10:11], s[6:7], 0, v[8:9]
	global_load_dwordx4 v[48:51], v[10:11], off
	global_load_dwordx4 v[52:55], v[10:11], off offset:16
	global_load_dwordx4 v[56:59], v[10:11], off offset:32
	global_load_dwordx4 v[60:63], v[10:11], off offset:48
	v_lshl_add_u64 v[10:11], s[8:9], 0, v[8:9]
	global_load_dwordx4 v[64:67], v[10:11], off
	global_load_dwordx4 v[68:71], v[10:11], off offset:16
	global_load_dwordx4 v[72:75], v[10:11], off offset:32
	global_load_dwordx4 v[76:79], v[10:11], off offset:48
	v_lshl_add_u64 v[10:11], s[10:11], 0, v[8:9]
	global_load_dwordx4 v[80:83], v[10:11], off
	global_load_dwordx4 v[84:87], v[10:11], off offset:16
	global_load_dwordx4 v[88:91], v[10:11], off offset:32
	global_load_dwordx4 v[92:95], v[10:11], off offset:48
	v_add_u32_e32 v1, s62, v1
	s_mov_b32 s18, 0xfffff
	v_cmp_lt_i32_e32 vcc, s18, v1
	v_add_u32_e32 v14, s28, v14
	s_or_b64 s[20:21], vcc, s[20:21]
	s_waitcnt vmcnt(0)
	v_cvt_f32_f16_e32 v2, v48
	v_cvt_f32_f16_e32 v3, v50
	v_cvt_f32_f16_e32 v4, v64
	v_cvt_f32_f16_e32 v5, v66
	v_fma_f32 v2, v32, v4, v2
	v_fma_f32 v3, v33, v5, v3
	v_cvt_f32_f16_e32 v4, v80
	v_cvt_f32_f16_e32 v5, v82
	v_fma_f32 v2, v40, v4, v2
	v_fma_f32 v3, v41, v5, v3
	v_cvt_f32_f16_e32 v4, v16
	v_cvt_f32_f16_sdwa v5, v16 dst_sel:DWORD dst_unused:UNUSED_PAD src0_sel:WORD_1
	v_mul_f32_e32 v2, v2, v4
	v_mul_f32_e32 v3, v3, v5
	v_cvt_pk_f16_f32 v16, v2, v3
	v_cvt_f32_f16_e32 v6, v52
	v_cvt_f32_f16_e32 v7, v54
	v_cvt_f32_f16_e32 v8, v68
	v_cvt_f32_f16_e32 v9, v70
	v_fma_f32 v6, v34, v8, v6
	v_fma_f32 v7, v35, v9, v7
	v_cvt_f32_f16_e32 v8, v84
	v_cvt_f32_f16_e32 v9, v86
	v_fma_f32 v6, v42, v8, v6
	v_fma_f32 v7, v43, v9, v7
	v_cvt_f32_f16_e32 v8, v17
	v_cvt_f32_f16_sdwa v9, v17 dst_sel:DWORD dst_unused:UNUSED_PAD src0_sel:WORD_1
	v_mul_f32_e32 v6, v6, v8
	v_mul_f32_e32 v7, v7, v9
	v_cvt_pk_f16_f32 v17, v6, v7
	v_cvt_f32_f16_e32 v2, v56
	v_cvt_f32_f16_e32 v3, v58
	v_cvt_f32_f16_e32 v4, v72
	v_cvt_f32_f16_e32 v5, v74
	v_fma_f32 v2, v36, v4, v2
	v_fma_f32 v3, v37, v5, v3
	v_cvt_f32_f16_e32 v4, v88
	v_cvt_f32_f16_e32 v5, v90
	v_fma_f32 v2, v44, v4, v2
	v_fma_f32 v3, v45, v5, v3
	v_cvt_f32_f16_e32 v4, v18
	v_cvt_f32_f16_sdwa v5, v18 dst_sel:DWORD dst_unused:UNUSED_PAD src0_sel:WORD_1
	v_mul_f32_e32 v2, v2, v4
	v_mul_f32_e32 v3, v3, v5
	v_cvt_pk_f16_f32 v18, v2, v3
	v_cvt_f32_f16_e32 v6, v60
	v_cvt_f32_f16_e32 v7, v62
	v_cvt_f32_f16_e32 v8, v76
	v_cvt_f32_f16_e32 v9, v78
	v_fma_f32 v6, v38, v8, v6
	v_fma_f32 v7, v39, v9, v7
	v_cvt_f32_f16_e32 v8, v92
	v_cvt_f32_f16_e32 v9, v94
	v_fma_f32 v6, v46, v8, v6
	v_fma_f32 v7, v47, v9, v7
	v_cvt_f32_f16_e32 v8, v19
	v_cvt_f32_f16_sdwa v9, v19 dst_sel:DWORD dst_unused:UNUSED_PAD src0_sel:WORD_1
	v_mul_f32_e32 v6, v6, v8
	v_mul_f32_e32 v7, v7, v9
	v_cvt_pk_f16_f32 v19, v6, v7
	v_cvt_f32_f16_sdwa v2, v48 dst_sel:DWORD dst_unused:UNUSED_PAD src0_sel:WORD_1
	v_cvt_f32_f16_sdwa v3, v50 dst_sel:DWORD dst_unused:UNUSED_PAD src0_sel:WORD_1
	v_cvt_f32_f16_sdwa v4, v64 dst_sel:DWORD dst_unused:UNUSED_PAD src0_sel:WORD_1
	v_cvt_f32_f16_sdwa v5, v66 dst_sel:DWORD dst_unused:UNUSED_PAD src0_sel:WORD_1
	v_fma_f32 v2, v32, v4, v2
	v_fma_f32 v3, v33, v5, v3
	v_cvt_f32_f16_sdwa v4, v80 dst_sel:DWORD dst_unused:UNUSED_PAD src0_sel:WORD_1
	v_cvt_f32_f16_sdwa v5, v82 dst_sel:DWORD dst_unused:UNUSED_PAD src0_sel:WORD_1
	v_fma_f32 v2, v40, v4, v2
	v_fma_f32 v3, v41, v5, v3
	v_cvt_f32_f16_e32 v4, v20
	v_cvt_f32_f16_sdwa v5, v20 dst_sel:DWORD dst_unused:UNUSED_PAD src0_sel:WORD_1
	v_mul_f32_e32 v2, v2, v4
	v_mul_f32_e32 v3, v3, v5
	v_cvt_pk_f16_f32 v20, v2, v3
	v_cvt_f32_f16_sdwa v6, v52 dst_sel:DWORD dst_unused:UNUSED_PAD src0_sel:WORD_1
	v_cvt_f32_f16_sdwa v7, v54 dst_sel:DWORD dst_unused:UNUSED_PAD src0_sel:WORD_1
; #define GAS __attribute__((address_space(1)))
; __device__ void lru_fixup_phase(const Params& p) {
;     ...
;         for (int r = 0; r < 4; ++r) {
;             float v[8];
; #pragma unroll
;             for (int j = 0; j < 8; ++j) { const float cfj = j < 4 ? cf0[j & 3] : cf1[j & 3], cbj = j < 4 ? cb0[j & 3] : cb1[j & 3]; const int e = (j & 1) * 4 + r;
;                 v[j] = (float)y[r][j] * ((float)hl[j >> 1][e] + (float)pf[j >> 1][e] * cfj + (float)pb[j >> 1][e] * cbj); }
;             u32x4 wv; wv.x = pk2(v[0], v[1]); wv.y = pk2(v[2], v[3]); wv.z = pk2(v[4], v[5]); wv.w = pk2(v[6], v[7]);
;             *(GAS u32x4*)(out + (size_t)(4 * tg + r) * DM + c8) = wv;
	v_cvt_f32_f16_sdwa v8, v68 dst_sel:DWORD dst_unused:UNUSED_PAD src0_sel:WORD_1
	v_cvt_f32_f16_sdwa v9, v70 dst_sel:DWORD dst_unused:UNUSED_PAD src0_sel:WORD_1
	v_fma_f32 v6, v34, v8, v6
	v_fma_f32 v7, v35, v9, v7
	v_cvt_f32_f16_sdwa v8, v84 dst_sel:DWORD dst_unused:UNUSED_PAD src0_sel:WORD_1
	v_cvt_f32_f16_sdwa v9, v86 dst_sel:DWORD dst_unused:UNUSED_PAD src0_sel:WORD_1
	v_fma_f32 v6, v42, v8, v6
	v_fma_f32 v7, v43, v9, v7
	v_cvt_f32_f16_e32 v8, v21
	v_cvt_f32_f16_sdwa v9, v21 dst_sel:DWORD dst_unused:UNUSED_PAD src0_sel:WORD_1
	v_mul_f32_e32 v6, v6, v8
	v_mul_f32_e32 v7, v7, v9
	v_cvt_pk_f16_f32 v21, v6, v7
	v_cvt_f32_f16_sdwa v2, v56 dst_sel:DWORD dst_unused:UNUSED_PAD src0_sel:WORD_1
	v_cvt_f32_f16_sdwa v3, v58 dst_sel:DWORD dst_unused:UNUSED_PAD src0_sel:WORD_1
	v_cvt_f32_f16_sdwa v4, v72 dst_sel:DWORD dst_unused:UNUSED_PAD src0_sel:WORD_1
	v_cvt_f32_f16_sdwa v5, v74 dst_sel:DWORD dst_unused:UNUSED_PAD src0_sel:WORD_1
	v_fma_f32 v2, v36, v4, v2
	v_fma_f32 v3, v37, v5, v3
	v_cvt_f32_f16_sdwa v4, v88 dst_sel:DWORD dst_unused:UNUSED_PAD src0_sel:WORD_1
	v_cvt_f32_f16_sdwa v5, v90 dst_sel:DWORD dst_unused:UNUSED_PAD src0_sel:WORD_1
	v_fma_f32 v2, v44, v4, v2
	v_fma_f32 v3, v45, v5, v3
	v_cvt_f32_f16_e32 v4, v22
	v_cvt_f32_f16_sdwa v5, v22 dst_sel:DWORD dst_unused:UNUSED_PAD src0_sel:WORD_1
	v_mul_f32_e32 v2, v2, v4
	v_mul_f32_e32 v3, v3, v5
	v_cvt_pk_f16_f32 v22, v2, v3
	v_cvt_f32_f16_sdwa v6, v60 dst_sel:DWORD dst_unused:UNUSED_PAD src0_sel:WORD_1
	v_cvt_f32_f16_sdwa v7, v62 dst_sel:DWORD dst_unused:UNUSED_PAD src0_sel:WORD_1
	v_cvt_f32_f16_sdwa v8, v76 dst_sel:DWORD dst_unused:UNUSED_PAD src0_sel:WORD_1
	v_cvt_f32_f16_sdwa v9, v78 dst_sel:DWORD dst_unused:UNUSED_PAD src0_sel:WORD_1
	v_fma_f32 v6, v38, v8, v6
	v_fma_f32 v7, v39, v9, v7
	v_cvt_f32_f16_sdwa v8, v92 dst_sel:DWORD dst_unused:UNUSED_PAD src0_sel:WORD_1
	v_cvt_f32_f16_sdwa v9, v94 dst_sel:DWORD dst_unused:UNUSED_PAD src0_sel:WORD_1
	v_fma_f32 v6, v46, v8, v6
	v_fma_f32 v7, v47, v9, v7
	v_cvt_f32_f16_e32 v8, v23
	v_cvt_f32_f16_sdwa v9, v23 dst_sel:DWORD dst_unused:UNUSED_PAD src0_sel:WORD_1
	v_mul_f32_e32 v6, v6, v8
	v_mul_f32_e32 v7, v7, v9
	v_cvt_pk_f16_f32 v23, v6, v7
	v_cvt_f32_f16_e32 v2, v49
	v_cvt_f32_f16_e32 v3, v51
	v_cvt_f32_f16_e32 v4, v65
	v_cvt_f32_f16_e32 v5, v67
	v_fma_f32 v2, v32, v4, v2
	v_fma_f32 v3, v33, v5, v3
	v_cvt_f32_f16_e32 v4, v81
	v_cvt_f32_f16_e32 v5, v83
	v_fma_f32 v2, v40, v4, v2
	v_fma_f32 v3, v41, v5, v3
	v_cvt_f32_f16_e32 v4, v24
	v_cvt_f32_f16_sdwa v5, v24 dst_sel:DWORD dst_unused:UNUSED_PAD src0_sel:WORD_1
	v_mul_f32_e32 v2, v2, v4
	v_mul_f32_e32 v3, v3, v5
	v_cvt_pk_f16_f32 v24, v2, v3
	v_cvt_f32_f16_e32 v6, v53
	v_cvt_f32_f16_e32 v7, v55
	v_cvt_f32_f16_e32 v8, v69
	v_cvt_f32_f16_e32 v9, v71
	v_fma_f32 v6, v34, v8, v6
	v_fma_f32 v7, v35, v9, v7
	v_cvt_f32_f16_e32 v8, v85
	v_cvt_f32_f16_e32 v9, v87
	v_fma_f32 v6, v42, v8, v6
	v_fma_f32 v7, v43, v9, v7
	v_cvt_f32_f16_e32 v8, v25
	v_cvt_f32_f16_sdwa v9, v25 dst_sel:DWORD dst_unused:UNUSED_PAD src0_sel:WORD_1
	v_mul_f32_e32 v6, v6, v8
	v_mul_f32_e32 v7, v7, v9
	v_cvt_pk_f16_f32 v25, v6, v7
	v_cvt_f32_f16_e32 v2, v57
	v_cvt_f32_f16_e32 v3, v59
	v_cvt_f32_f16_e32 v4, v73
	v_cvt_f32_f16_e32 v5, v75
	v_fma_f32 v2, v36, v4, v2
	v_fma_f32 v3, v37, v5, v3
	v_cvt_f32_f16_e32 v4, v89
	v_cvt_f32_f16_e32 v5, v91
	v_fma_f32 v2, v44, v4, v2
	v_fma_f32 v3, v45, v5, v3
	v_cvt_f32_f16_e32 v4, v26
	v_cvt_f32_f16_sdwa v5, v26 dst_sel:DWORD dst_unused:UNUSED_PAD src0_sel:WORD_1
	v_mul_f32_e32 v2, v2, v4
	v_mul_f32_e32 v3, v3, v5
	v_cvt_pk_f16_f32 v26, v2, v3
	v_cvt_f32_f16_e32 v6, v61
	v_cvt_f32_f16_e32 v7, v63
	v_cvt_f32_f16_e32 v8, v77
	v_cvt_f32_f16_e32 v9, v79
	v_fma_f32 v6, v38, v8, v6
; #define GAS __attribute__((address_space(1)))
; __device__ void lru_fixup_phase(const Params& p) {
;     ...
;         for (int r = 0; r < 4; ++r) {
;             float v[8];
; #pragma unroll
;             for (int j = 0; j < 8; ++j) { const float cfj = j < 4 ? cf0[j & 3] : cf1[j & 3], cbj = j < 4 ? cb0[j & 3] : cb1[j & 3]; const int e = (j & 1) * 4 + r;
;                 v[j] = (float)y[r][j] * ((float)hl[j >> 1][e] + (float)pf[j >> 1][e] * cfj + (float)pb[j >> 1][e] * cbj); }
;             u32x4 wv; wv.x = pk2(v[0], v[1]); wv.y = pk2(v[2], v[3]); wv.z = pk2(v[4], v[5]); wv.w = pk2(v[6], v[7]);
;             *(GAS u32x4*)(out + (size_t)(4 * tg + r) * DM + c8) = wv;
;         }
;     }
	v_fma_f32 v7, v39, v9, v7
	v_cvt_f32_f16_e32 v8, v93
	v_cvt_f32_f16_e32 v9, v95
	v_fma_f32 v6, v46, v8, v6
	v_fma_f32 v7, v47, v9, v7
	v_cvt_f32_f16_e32 v8, v27
	v_cvt_f32_f16_sdwa v9, v27 dst_sel:DWORD dst_unused:UNUSED_PAD src0_sel:WORD_1
	v_mul_f32_e32 v6, v6, v8
	v_mul_f32_e32 v7, v7, v9
	v_cvt_pk_f16_f32 v27, v6, v7
	v_cvt_f32_f16_sdwa v2, v49 dst_sel:DWORD dst_unused:UNUSED_PAD src0_sel:WORD_1
	v_cvt_f32_f16_sdwa v3, v51 dst_sel:DWORD dst_unused:UNUSED_PAD src0_sel:WORD_1
	v_cvt_f32_f16_sdwa v4, v65 dst_sel:DWORD dst_unused:UNUSED_PAD src0_sel:WORD_1
	v_cvt_f32_f16_sdwa v5, v67 dst_sel:DWORD dst_unused:UNUSED_PAD src0_sel:WORD_1
	v_fma_f32 v2, v32, v4, v2
	v_fma_f32 v3, v33, v5, v3
	v_cvt_f32_f16_sdwa v4, v81 dst_sel:DWORD dst_unused:UNUSED_PAD src0_sel:WORD_1
	v_cvt_f32_f16_sdwa v5, v83 dst_sel:DWORD dst_unused:UNUSED_PAD src0_sel:WORD_1
	v_fma_f32 v2, v40, v4, v2
	v_fma_f32 v3, v41, v5, v3
	v_cvt_f32_f16_e32 v4, v28
	v_cvt_f32_f16_sdwa v5, v28 dst_sel:DWORD dst_unused:UNUSED_PAD src0_sel:WORD_1
	v_mul_f32_e32 v2, v2, v4
	v_mul_f32_e32 v3, v3, v5
	v_cvt_pk_f16_f32 v28, v2, v3
	v_cvt_f32_f16_sdwa v6, v53 dst_sel:DWORD dst_unused:UNUSED_PAD src0_sel:WORD_1
	v_cvt_f32_f16_sdwa v7, v55 dst_sel:DWORD dst_unused:UNUSED_PAD src0_sel:WORD_1
	v_cvt_f32_f16_sdwa v8, v69 dst_sel:DWORD dst_unused:UNUSED_PAD src0_sel:WORD_1
	v_cvt_f32_f16_sdwa v9, v71 dst_sel:DWORD dst_unused:UNUSED_PAD src0_sel:WORD_1
	v_fma_f32 v6, v34, v8, v6
	v_fma_f32 v7, v35, v9, v7
	v_cvt_f32_f16_sdwa v8, v85 dst_sel:DWORD dst_unused:UNUSED_PAD src0_sel:WORD_1
	v_cvt_f32_f16_sdwa v9, v87 dst_sel:DWORD dst_unused:UNUSED_PAD src0_sel:WORD_1
	v_fma_f32 v6, v42, v8, v6
	v_fma_f32 v7, v43, v9, v7
	v_cvt_f32_f16_e32 v8, v29
	v_cvt_f32_f16_sdwa v9, v29 dst_sel:DWORD dst_unused:UNUSED_PAD src0_sel:WORD_1
	v_mul_f32_e32 v6, v6, v8
	v_mul_f32_e32 v7, v7, v9
	v_cvt_pk_f16_f32 v29, v6, v7
	v_cvt_f32_f16_sdwa v2, v57 dst_sel:DWORD dst_unused:UNUSED_PAD src0_sel:WORD_1
	v_cvt_f32_f16_sdwa v3, v59 dst_sel:DWORD dst_unused:UNUSED_PAD src0_sel:WORD_1
	v_cvt_f32_f16_sdwa v4, v73 dst_sel:DWORD dst_unused:UNUSED_PAD src0_sel:WORD_1
	v_cvt_f32_f16_sdwa v5, v75 dst_sel:DWORD dst_unused:UNUSED_PAD src0_sel:WORD_1
	v_fma_f32 v2, v36, v4, v2
	v_fma_f32 v3, v37, v5, v3
	v_cvt_f32_f16_sdwa v4, v89 dst_sel:DWORD dst_unused:UNUSED_PAD src0_sel:WORD_1
	v_cvt_f32_f16_sdwa v5, v91 dst_sel:DWORD dst_unused:UNUSED_PAD src0_sel:WORD_1
	v_fma_f32 v2, v44, v4, v2
	v_fma_f32 v3, v45, v5, v3
	v_cvt_f32_f16_e32 v4, v30
	v_cvt_f32_f16_sdwa v5, v30 dst_sel:DWORD dst_unused:UNUSED_PAD src0_sel:WORD_1
	v_mul_f32_e32 v2, v2, v4
	v_mul_f32_e32 v3, v3, v5
	v_cvt_pk_f16_f32 v30, v2, v3
	v_cvt_f32_f16_sdwa v6, v61 dst_sel:DWORD dst_unused:UNUSED_PAD src0_sel:WORD_1
	v_cvt_f32_f16_sdwa v7, v63 dst_sel:DWORD dst_unused:UNUSED_PAD src0_sel:WORD_1
	v_cvt_f32_f16_sdwa v8, v77 dst_sel:DWORD dst_unused:UNUSED_PAD src0_sel:WORD_1
	v_cvt_f32_f16_sdwa v9, v79 dst_sel:DWORD dst_unused:UNUSED_PAD src0_sel:WORD_1
	v_fma_f32 v6, v38, v8, v6
	v_fma_f32 v7, v39, v9, v7
	v_cvt_f32_f16_sdwa v8, v93 dst_sel:DWORD dst_unused:UNUSED_PAD src0_sel:WORD_1
	v_cvt_f32_f16_sdwa v9, v95 dst_sel:DWORD dst_unused:UNUSED_PAD src0_sel:WORD_1
	v_fma_f32 v6, v46, v8, v6
	v_fma_f32 v7, v47, v9, v7
	v_cvt_f32_f16_e32 v8, v31
	v_cvt_f32_f16_sdwa v9, v31 dst_sel:DWORD dst_unused:UNUSED_PAD src0_sel:WORD_1
	v_mul_f32_e32 v6, v6, v8
	v_mul_f32_e32 v7, v7, v9
	v_cvt_pk_f16_f32 v31, v6, v7
	global_store_dwordx4 v[96:97], v[16:19], off offset:-4096
	global_store_dwordx4 v[96:97], v[20:23], off
	global_store_dwordx4 v[98:99], v[24:27], off offset:-4096
	global_store_dwordx4 v[98:99], v[28:31], off
	s_andn2_b64 exec, exec, s[20:21]
	s_cbranch_execnz .Lfix_loop
